# baseline (speedup 1.0000x reference)
; #define DSR(dst, addr, OFF) asm volatile("ds_read_b128 %0, %1 offset:%2" : "=&v"(dst) : "v"(addr), "i"(OFF) : "memory")
; template <int EPI>
; __device__ __forceinline__ void gemm_phase(const Params& p, const u16* __restrict__ A, const u16* __restrict__ Bt, int K, int nN,
;                            u16* __restrict__ Cout, int ldc) {
;     ...
;     for (int t = 0; t < nt; ++t) {
;       const int cur = t & 1, nb = cur ^ 1;
;       const bool last = (t + 1 == nt);
;       const bool dostage = !last || has_next;
;       const u16* pa = last ? Abn : Ab + (t + 1) * BK;
;       const u16* pb = last ? Bbn : Bb + (t + 1) * BK;
;       bf16x8 Ar[3], Bq[2][4];
;       const unsigned la_u = lds0 + (unsigned)(cur * STAGE_B + aoff), lb_u = lds0 + (unsigned)(cur * STAGE_B + boff);
;     ...
;       DSR(Bq[0][0], lb_u, 0); DSR(Bq[0][1], lb_u, 2048); DSR(Bq[0][2], lb_u, 4096); DSR(Bq[0][3], lb_u, 6144);
;       DSR(Ar[0], la_u, 0); DSR(Ar[1], la_u, 2048);
;     ...
;       GSTEP(0, 2); GSTEP(1, 6); GSTEP(2, 6); GSTEP(3, 6); GSTEP(4, 2); GSTEP(5, 2); GSTEP(6, 2); GSTEP(7, 2);
;       GSTEP(8, 2); GSTEP(9, 2); GSTEP(10, 2); GSTEP(11, 2); GSTEP(12, 2); GSTEP(13, 2); GSTEP(14, 1); GSTEP(15, 0);
.LBB0_859:
	ds_read_b128 v[0:3], v194 offset:0
	ds_read_b128 v[4:7], v194 offset:0x800
	ds_read_b128 v[8:11], v194 offset:0x1000
	ds_read_b128 v[12:15], v194 offset:0x1800
	ds_read_b128 v[16:19], v193 offset:0
	ds_read_b128 v[20:23], v193 offset:0x800
	ds_read_b128 v[24:27], v193 offset:0x1000
	s_waitcnt lgkmcnt(2)
	s_setprio 1
	v_mfma_f32_16x16x32_bf16 v[28:31], v[16:19], v[0:3], 0
	v_mfma_f32_16x16x32_bf16 v[32:35], v[16:19], v[4:7], 0
	v_mfma_f32_16x16x32_bf16 v[36:39], v[16:19], v[8:11], 0
	v_mfma_f32_16x16x32_bf16 v[16:19], v[16:19], v[12:15], 0
	s_setprio 0
	v_mov_b32_e32 v40, v176
	v_mov_b32_e32 v41, v172
	v_lshl_add_u64 v[40:41], v[40:41], 1, s[30:31]
	v_readfirstlane_b32 s17, v198
	v_lshl_add_u64 v[40:41], v[40:41], 0, s[62:63]
	s_mov_b32 m0, s17
	s_nop 0
	global_load_lds_dwordx4 v[40:41], off
	ds_read_b128 v[40:43], v193 offset:0x1800
	ds_read_b128 v[130:133], v194 offset:0x400
	ds_read_b128 v[134:137], v194 offset:0xc00
	ds_read_b128 v[138:141], v194 offset:0x1400
	ds_read_b128 v[142:145], v194 offset:0x1c00
	s_waitcnt lgkmcnt(6)
	s_setprio 1
	v_mfma_f32_16x16x32_bf16 v[44:47], v[20:23], v[0:3], 0
	v_mfma_f32_16x16x32_bf16 v[48:51], v[20:23], v[4:7], 0
	v_mfma_f32_16x16x32_bf16 v[52:55], v[20:23], v[8:11], 0
	v_mfma_f32_16x16x32_bf16 v[20:23], v[20:23], v[12:15], 0
	s_setprio 0
	v_mov_b32_e32 v56, v178
	v_mov_b32_e32 v57, v172
	v_lshl_add_u64 v[56:57], v[56:57], 1, s[30:31]
	v_readfirstlane_b32 s17, v199
	v_lshl_add_u64 v[56:57], v[56:57], 0, s[62:63]
	s_mov_b32 m0, s17
	s_nop 0
	global_load_lds_dwordx4 v[56:57], off
	ds_read_b128 v[56:59], v193 offset:0x2000
	s_waitcnt lgkmcnt(6)
	s_setprio 1
	v_mfma_f32_16x16x32_bf16 v[60:63], v[24:27], v[0:3], 0
	v_mfma_f32_16x16x32_bf16 v[64:67], v[24:27], v[4:7], 0
	v_mfma_f32_16x16x32_bf16 v[68:71], v[24:27], v[8:11], 0
	v_mfma_f32_16x16x32_bf16 v[24:27], v[24:27], v[12:15], 0
	s_setprio 0
	v_mov_b32_e32 v72, v180
	v_mov_b32_e32 v73, v172
	v_lshl_add_u64 v[72:73], v[72:73], 1, s[30:31]
	v_readfirstlane_b32 s17, v200
	v_lshl_add_u64 v[72:73], v[72:73], 0, s[62:63]
	s_mov_b32 m0, s17
	s_nop 0
	global_load_lds_dwordx4 v[72:73], off
	ds_read_b128 v[72:75], v193 offset:0x2800
	s_waitcnt lgkmcnt(6)
	s_setprio 1
	v_mfma_f32_16x16x32_bf16 v[76:79], v[40:43], v[0:3], 0
	v_mfma_f32_16x16x32_bf16 v[146:149], v[40:43], v[4:7], 0
	v_mfma_f32_16x16x32_bf16 v[150:153], v[40:43], v[8:11], 0
	v_mfma_f32_16x16x32_bf16 v[40:43], v[40:43], v[12:15], 0
	s_setprio 0
	v_mov_b32_e32 v80, v191
	v_mov_b32_e32 v81, v172
	v_lshl_add_u64 v[80:81], v[80:81], 1, s[30:31]
	v_readfirstlane_b32 s17, v201
	v_lshl_add_u64 v[80:81], v[80:81], 0, s[62:63]
	s_mov_b32 m0, s17
	s_nop 0
	global_load_lds_dwordx4 v[80:81], off
	ds_read_b128 v[80:83], v193 offset:0x3000
	s_waitcnt lgkmcnt(2)
	s_setprio 1
	v_mfma_f32_16x16x32_bf16 v[154:157], v[56:59], v[0:3], 0
	v_mfma_f32_16x16x32_bf16 v[158:161], v[56:59], v[4:7], 0
	v_mfma_f32_16x16x32_bf16 v[162:165], v[56:59], v[8:11], 0
	v_mfma_f32_16x16x32_bf16 v[166:169], v[56:59], v[12:15], 0
	s_setprio 0
	v_mov_b32_e32 v56, v176
	v_mov_b32_e32 v57, v172
	v_lshl_add_u64 v[56:57], v[56:57], 1, s[28:29]
	v_readfirstlane_b32 s17, v206
	v_lshl_add_u64 v[56:57], v[56:57], 0, s[62:63]
	s_mov_b32 m0, s17
	s_nop 0
	global_load_lds_dwordx4 v[56:57], off
	ds_read_b128 v[56:59], v193 offset:0x3800
	s_waitcnt lgkmcnt(2)
	s_setprio 1
	v_mfma_f32_16x16x32_bf16 v[208:211], v[72:75], v[0:3], 0
	v_mfma_f32_16x16x32_bf16 v[212:215], v[72:75], v[4:7], 0
	v_mfma_f32_16x16x32_bf16 v[216:219], v[72:75], v[8:11], 0
	v_mfma_f32_16x16x32_bf16 v[220:223], v[72:75], v[12:15], 0
	s_setprio 0
	v_mov_b32_e32 v72, v178
	v_mov_b32_e32 v73, v172
	v_lshl_add_u64 v[72:73], v[72:73], 1, s[28:29]
	v_readfirstlane_b32 s17, v202
	v_lshl_add_u64 v[72:73], v[72:73], 0, s[62:63]
	s_mov_b32 m0, s17
	s_nop 0
	global_load_lds_dwordx4 v[72:73], off
	ds_read_b128 v[72:75], v193 offset:0x400
	s_waitcnt lgkmcnt(2)
	s_setprio 1
	v_mfma_f32_16x16x32_bf16 v[224:227], v[80:83], v[0:3], 0
	v_mfma_f32_16x16x32_bf16 v[228:231], v[80:83], v[4:7], 0
	v_mfma_f32_16x16x32_bf16 v[232:235], v[80:83], v[8:11], 0
	v_mfma_f32_16x16x32_bf16 v[236:239], v[80:83], v[12:15], 0
	s_setprio 0
	v_mov_b32_e32 v80, v180
	v_mov_b32_e32 v81, v172
	v_lshl_add_u64 v[80:81], v[80:81], 1, s[28:29]
	v_readfirstlane_b32 s17, v203
	v_lshl_add_u64 v[80:81], v[80:81], 0, s[62:63]
	s_mov_b32 m0, s17
	s_nop 0
	global_load_lds_dwordx4 v[80:81], off
	ds_read_b128 v[80:83], v193 offset:0xc00
	s_waitcnt lgkmcnt(2)
	s_setprio 1
	v_mfma_f32_16x16x32_bf16 v[0:3], v[56:59], v[0:3], 0
	v_mfma_f32_16x16x32_bf16 v[4:7], v[56:59], v[4:7], 0
	v_mfma_f32_16x16x32_bf16 v[240:243], v[56:59], v[8:11], 0
	v_mfma_f32_16x16x32_bf16 v[244:247], v[56:59], v[12:15], 0
	s_setprio 0
	v_mov_b32_e32 v8, v191
	v_mov_b32_e32 v9, v172
	v_lshl_add_u64 v[8:9], v[8:9], 1, s[28:29]
	v_readfirstlane_b32 s17, v204
	v_lshl_add_u64 v[8:9], v[8:9], 0, s[62:63]
	s_mov_b32 m0, s17
	s_nop 0
	global_load_lds_dwordx4 v[8:9], off
	ds_read_b128 v[8:11], v193 offset:0x1400
	s_waitcnt lgkmcnt(2)
	s_setprio 1
	v_mfma_f32_16x16x32_bf16 v[124:127], v[72:75], v[130:133], v[28:31]
	v_mfma_f32_16x16x32_bf16 v[120:123], v[72:75], v[134:137], v[32:35]
	v_mfma_f32_16x16x32_bf16 v[116:119], v[72:75], v[138:141], v[36:39]
	v_mfma_f32_16x16x32_bf16 v[112:115], v[72:75], v[142:145], v[16:19]
	s_setprio 0
	ds_read_b128 v[12:15], v193 offset:0x1c00
	s_waitcnt lgkmcnt(2)
	s_setprio 1
	v_mfma_f32_16x16x32_bf16 v[108:111], v[80:83], v[130:133], v[44:47]
	v_mfma_f32_16x16x32_bf16 v[104:107], v[80:83], v[134:137], v[48:51]
	v_mfma_f32_16x16x32_bf16 v[100:103], v[80:83], v[138:141], v[52:55]
	v_mfma_f32_16x16x32_bf16 v[96:99], v[80:83], v[142:145], v[20:23]
	s_setprio 0
	ds_read_b128 v[16:19], v193 offset:0x2400
	s_waitcnt lgkmcnt(2)
; __device__ __forceinline__ float rsq_(float x) { return __builtin_amdgcn_rsqf(x); }
; #define WAIT_V(n) asm volatile("s_waitcnt vmcnt(%0)" ::"n"(n) : "memory")
; #define DSR(dst, addr, OFF) asm volatile("ds_read_b128 %0, %1 offset:%2" : "=&v"(dst) : "v"(addr), "i"(OFF) : "memory")
; template <int EPI>
; __device__ __forceinline__ void gemm_phase(const Params& p, const u16* __restrict__ A, const u16* __restrict__ Bt, int K, int nN,
;                            u16* __restrict__ Cout, int ldc) {
;     ...
;     for (int t = 0; t < nt; ++t) {
;       const int cur = t & 1, nb = cur ^ 1;
;       const bool last = (t + 1 == nt);
;       const bool dostage = !last || has_next;
;       const u16* pa = last ? Abn : Ab + (t + 1) * BK;
;       const u16* pb = last ? Bbn : Bb + (t + 1) * BK;
;       bf16x8 Ar[3], Bq[2][4];
;       const unsigned la_u = lds0 + (unsigned)(cur * STAGE_B + aoff), lb_u = lds0 + (unsigned)(cur * STAGE_B + boff);
;     ...
;       DSR(Bq[0][0], lb_u, 0); DSR(Bq[0][1], lb_u, 2048); DSR(Bq[0][2], lb_u, 4096); DSR(Bq[0][3], lb_u, 6144);
;       DSR(Ar[0], la_u, 0); DSR(Ar[1], la_u, 2048);
;     ...
;       GSTEP(0, 2); GSTEP(1, 6); GSTEP(2, 6); GSTEP(3, 6); GSTEP(4, 2); GSTEP(5, 2); GSTEP(6, 2); GSTEP(7, 2);
;       GSTEP(8, 2); GSTEP(9, 2); GSTEP(10, 2); GSTEP(11, 2); GSTEP(12, 2); GSTEP(13, 2); GSTEP(14, 1); GSTEP(15, 0);
;       WAIT_V(0);
;       if (EPI != EPI_SS && t == 0 && tid < 256) rsl[tid] = rsq_(ssv * (1.f / DM) + EPS);
;       __syncthreads();
	s_setprio 1
	v_mfma_f32_16x16x32_bf16 v[92:95], v[8:11], v[130:133], v[60:63]
	v_mfma_f32_16x16x32_bf16 v[88:91], v[8:11], v[134:137], v[64:67]
	v_mfma_f32_16x16x32_bf16 v[84:87], v[8:11], v[138:141], v[68:71]
	v_mfma_f32_16x16x32_bf16 v[80:83], v[8:11], v[142:145], v[24:27]
	s_setprio 0
	ds_read_b128 v[8:11], v193 offset:0x2c00
	s_waitcnt lgkmcnt(2)
	s_setprio 1
	v_mfma_f32_16x16x32_bf16 v[76:79], v[12:15], v[130:133], v[76:79]
	v_mfma_f32_16x16x32_bf16 v[72:75], v[12:15], v[134:137], v[146:149]
	v_mfma_f32_16x16x32_bf16 v[68:71], v[12:15], v[138:141], v[150:153]
	v_mfma_f32_16x16x32_bf16 v[64:67], v[12:15], v[142:145], v[40:43]
	s_setprio 0
	ds_read_b128 v[12:15], v193 offset:0x3400
	s_waitcnt lgkmcnt(2)
	s_setprio 1
	v_mfma_f32_16x16x32_bf16 v[60:63], v[16:19], v[130:133], v[154:157]
	v_mfma_f32_16x16x32_bf16 v[56:59], v[16:19], v[134:137], v[158:161]
	v_mfma_f32_16x16x32_bf16 v[52:55], v[16:19], v[138:141], v[162:165]
	v_mfma_f32_16x16x32_bf16 v[48:51], v[16:19], v[142:145], v[166:169]
	s_setprio 0
	ds_read_b128 v[146:149], v193 offset:0x3c00
	s_waitcnt lgkmcnt(2)
	s_setprio 1
	v_mfma_f32_16x16x32_bf16 v[44:47], v[8:11], v[130:133], v[208:211]
	v_mfma_f32_16x16x32_bf16 v[40:43], v[8:11], v[134:137], v[212:215]
	v_mfma_f32_16x16x32_bf16 v[36:39], v[8:11], v[138:141], v[216:219]
	v_mfma_f32_16x16x32_bf16 v[32:35], v[8:11], v[142:145], v[220:223]
	s_setprio 0
	s_waitcnt lgkmcnt(1)
	s_setprio 1
	v_mfma_f32_16x16x32_bf16 v[28:31], v[12:15], v[130:133], v[224:227]
	v_mfma_f32_16x16x32_bf16 v[24:27], v[12:15], v[134:137], v[228:231]
	v_mfma_f32_16x16x32_bf16 v[20:23], v[12:15], v[138:141], v[232:235]
	v_mfma_f32_16x16x32_bf16 v[16:19], v[12:15], v[142:145], v[236:239]
	s_setprio 0
	s_waitcnt lgkmcnt(0)
	s_setprio 1
	v_mfma_f32_16x16x32_bf16 v[12:15], v[146:149], v[130:133], v[0:3]
	v_mfma_f32_16x16x32_bf16 v[8:11], v[146:149], v[134:137], v[4:7]
	v_mfma_f32_16x16x32_bf16 v[4:7], v[146:149], v[138:141], v[240:243]
	v_mfma_f32_16x16x32_bf16 v[0:3], v[146:149], v[142:145], v[244:247]
	s_setprio 0
	s_waitcnt vmcnt(0)
	s_and_saveexec_b64 s[28:29], s[0:1]
	v_rsq_f32_e32 v128, v128
	ds_write_b32 v195, v128
	s_or_b64 exec, exec, s[28:29]
	s_add_u32 s17, s42, s26
	s_addc_u32 s19, s43, s27
	s_add_u32 s30, s44, s2
	s_addc_u32 s31, s45, s3
	s_mov_b32 s34, -15
	s_waitcnt vmcnt(0) lgkmcnt(0)
	s_barrier
	v_or_b32_e32 v209, 0x10000, v194
	v_add_u32_e32 v207, 0x10000, v193
	ds_read_b128 v[212:215], v209 offset:0
	ds_read_b128 v[216:219], v209 offset:2048
	ds_read_b128 v[220:223], v209 offset:4096
	ds_read_b128 v[224:227], v209 offset:6144
	ds_read_b128 v[228:231], v207 offset:0
	ds_read_b128 v[168:171], v207 offset:2048
	ds_read_b128 v[160:163], v207 offset:4096
	v_readfirstlane_b32 s35, v175
	v_lshlrev_b32_e32 v232, 1, v176
	v_lshlrev_b32_e32 v233, 1, v178
	v_lshlrev_b32_e32 v234, 1, v180
	v_lshlrev_b32_e32 v235, 1, v191
	s_cmp_lg_u32 s34, -1
	s_cselect_b32 s28, s30, s22
	s_cselect_b32 s29, s31, s23
	s_cselect_b32 s26, s17, s24
	s_cselect_b32 s27, s19, s25
	s_cselect_b64 vcc, -1, s[20:21]
	v_readfirstlane_b32 s36, v175
	s_lshr_b32 s36, s36, 12
.Lwi_head:
	s_waitcnt lgkmcnt(2)
	s_setprio 1
	v_mfma_f32_16x16x32_bf16 v[124:127], v[228:231], v[212:215], v[124:127]
	v_mfma_f32_16x16x32_bf16 v[120:123], v[228:231], v[216:219], v[120:123]
	v_mfma_f32_16x16x32_bf16 v[116:119], v[228:231], v[220:223], v[116:119]
	v_mfma_f32_16x16x32_bf16 v[112:115], v[228:231], v[224:227], v[112:115]
	s_setprio 0
	s_cbranch_vccz .Lwi_sk17
	s_cmp_eq_u32 s36, 0
	s_cbranch_scc0 .Lwi_sk17
	s_mov_b32 m0, s35
	s_nop 0
	global_load_lds_dwordx4 v232, s[28:29]
	s_add_u32 m0, s35, 0x2000
	s_nop 0
	global_load_lds_dwordx4 v233, s[28:29]
.Lwi_sk17:
	ds_read_b128 v[164:167], v207 offset:6144
	ds_read_b128 v[128:131], v209 offset:1024
	ds_read_b128 v[132:135], v209 offset:3072
	ds_read_b128 v[136:139], v209 offset:5120
	ds_read_b128 v[140:143], v209 offset:7168
	s_waitcnt lgkmcnt(6)
	s_setprio 1
	v_mfma_f32_16x16x32_bf16 v[108:111], v[168:171], v[212:215], v[108:111]
	v_mfma_f32_16x16x32_bf16 v[104:107], v[168:171], v[216:219], v[104:107]
	v_mfma_f32_16x16x32_bf16 v[100:103], v[168:171], v[220:223], v[100:103]
	v_mfma_f32_16x16x32_bf16 v[96:99], v[168:171], v[224:227], v[96:99]
	s_setprio 0
	s_cbranch_vccz .Lwi_sk18
	s_cmp_eq_u32 s36, 0
	s_cbranch_scc0 .Lwi_sk18
	s_add_u32 m0, s35, 0x4000
	s_nop 0
	global_load_lds_dwordx4 v234, s[28:29]
	s_add_u32 m0, s35, 0x6000
	s_nop 0
	global_load_lds_dwordx4 v235, s[28:29]
.Lwi_sk18:
	ds_read_b128 v[168:171], v207 offset:8192
	s_waitcnt lgkmcnt(6)
	s_setprio 1
	v_mfma_f32_16x16x32_bf16 v[92:95], v[160:163], v[212:215], v[92:95]
	v_mfma_f32_16x16x32_bf16 v[88:91], v[160:163], v[216:219], v[88:91]
	v_mfma_f32_16x16x32_bf16 v[84:87], v[160:163], v[220:223], v[84:87]
	v_mfma_f32_16x16x32_bf16 v[80:83], v[160:163], v[224:227], v[80:83]
	s_setprio 0
	s_cbranch_vccz .Lwi_sk19
	s_cmp_eq_u32 s36, 0
	s_cbranch_scc0 .Lwi_sk19
	s_add_u32 m0, s35, 0x8000
	s_nop 0
	global_load_lds_dwordx4 v232, s[26:27]
	s_add_u32 m0, s35, 0xa000
	s_nop 0
	global_load_lds_dwordx4 v233, s[26:27]
.Lwi_sk19:
	ds_read_b128 v[160:163], v207 offset:10240
	s_waitcnt lgkmcnt(6)
	s_setprio 1
	v_mfma_f32_16x16x32_bf16 v[76:79], v[164:167], v[212:215], v[76:79]
	v_mfma_f32_16x16x32_bf16 v[72:75], v[164:167], v[216:219], v[72:75]
	v_mfma_f32_16x16x32_bf16 v[68:71], v[164:167], v[220:223], v[68:71]
	v_mfma_f32_16x16x32_bf16 v[64:67], v[164:167], v[224:227], v[64:67]
	s_setprio 0
	s_cbranch_vccz .Lwi_sk20
	s_cmp_eq_u32 s36, 0
	s_cbranch_scc0 .Lwi_sk20
	s_add_u32 m0, s35, 0xc000
	s_nop 0
	global_load_lds_dwordx4 v234, s[26:27]
	s_add_u32 m0, s35, 0xe000
	s_nop 0
	global_load_lds_dwordx4 v235, s[26:27]
; __device__ __forceinline__ float rsq_(float x) { return __builtin_amdgcn_rsqf(x); }
; #define WAIT_V(n) asm volatile("s_waitcnt vmcnt(%0)" ::"n"(n) : "memory")
; template <int EPI>
; __device__ __forceinline__ void gemm_phase(const Params& p, const u16* __restrict__ A, const u16* __restrict__ Bt, int K, int nN,
;                            u16* __restrict__ Cout, int ldc) {
;     ...
;       GSTEP(0, 2); GSTEP(1, 6); GSTEP(2, 6); GSTEP(3, 6); GSTEP(4, 2); GSTEP(5, 2); GSTEP(6, 2); GSTEP(7, 2);
;       GSTEP(8, 2); GSTEP(9, 2); GSTEP(10, 2); GSTEP(11, 2); GSTEP(12, 2); GSTEP(13, 2); GSTEP(14, 1); GSTEP(15, 0);
;       WAIT_V(0);
;       if (EPI != EPI_SS && t == 0 && tid < 256) rsl[tid] = rsq_(ssv * (1.f / DM) + EPS);
;       __syncthreads();
.Lwi_sk20:
	ds_read_b128 v[164:167], v207 offset:12288
	s_waitcnt lgkmcnt(2)
	s_setprio 1
	v_mfma_f32_16x16x32_bf16 v[60:63], v[168:171], v[212:215], v[60:63]
	v_mfma_f32_16x16x32_bf16 v[56:59], v[168:171], v[216:219], v[56:59]
	v_mfma_f32_16x16x32_bf16 v[52:55], v[168:171], v[220:223], v[52:55]
	v_mfma_f32_16x16x32_bf16 v[48:51], v[168:171], v[224:227], v[48:51]
	s_setprio 0
	s_cbranch_vccz .Lwi_sk21
	s_cmp_eq_u32 s36, 1
	s_cbranch_scc0 .Lwi_sk21
	s_mov_b32 m0, s35
	s_nop 0
	global_load_lds_dwordx4 v232, s[28:29]
	s_add_u32 m0, s35, 0x2000
	s_nop 0
	global_load_lds_dwordx4 v233, s[28:29]
.Lwi_sk21:
	ds_read_b128 v[168:171], v207 offset:14336
	s_waitcnt lgkmcnt(2)
	s_setprio 1
	v_mfma_f32_16x16x32_bf16 v[44:47], v[160:163], v[212:215], v[44:47]
	v_mfma_f32_16x16x32_bf16 v[40:43], v[160:163], v[216:219], v[40:43]
	v_mfma_f32_16x16x32_bf16 v[36:39], v[160:163], v[220:223], v[36:39]
	v_mfma_f32_16x16x32_bf16 v[32:35], v[160:163], v[224:227], v[32:35]
	s_setprio 0
	s_cbranch_vccz .Lwi_sk22
	s_cmp_eq_u32 s36, 1
	s_cbranch_scc0 .Lwi_sk22
	s_add_u32 m0, s35, 0x4000
	s_nop 0
	global_load_lds_dwordx4 v234, s[28:29]
	s_add_u32 m0, s35, 0x6000
	s_nop 0
	global_load_lds_dwordx4 v235, s[28:29]
.Lwi_sk22:
	ds_read_b128 v[160:163], v207 offset:1024
	s_waitcnt lgkmcnt(2)
	s_setprio 1
	v_mfma_f32_16x16x32_bf16 v[28:31], v[164:167], v[212:215], v[28:31]
	v_mfma_f32_16x16x32_bf16 v[24:27], v[164:167], v[216:219], v[24:27]
	v_mfma_f32_16x16x32_bf16 v[20:23], v[164:167], v[220:223], v[20:23]
	v_mfma_f32_16x16x32_bf16 v[16:19], v[164:167], v[224:227], v[16:19]
	s_setprio 0
	s_cbranch_vccz .Lwi_sk23
	s_cmp_eq_u32 s36, 1
	s_cbranch_scc0 .Lwi_sk23
	s_add_u32 m0, s35, 0x8000
	s_nop 0
	global_load_lds_dwordx4 v232, s[26:27]
	s_add_u32 m0, s35, 0xa000
	s_nop 0
	global_load_lds_dwordx4 v233, s[26:27]
.Lwi_sk23:
	ds_read_b128 v[164:167], v207 offset:3072
	s_waitcnt lgkmcnt(2)
	s_setprio 1
	v_mfma_f32_16x16x32_bf16 v[12:15], v[168:171], v[212:215], v[12:15]
	v_mfma_f32_16x16x32_bf16 v[8:11], v[168:171], v[216:219], v[8:11]
	v_mfma_f32_16x16x32_bf16 v[4:7], v[168:171], v[220:223], v[4:7]
	v_mfma_f32_16x16x32_bf16 v[0:3], v[168:171], v[224:227], v[0:3]
	s_setprio 0
	s_cbranch_vccz .Lwi_sk24
	s_cmp_eq_u32 s36, 1
	s_cbranch_scc0 .Lwi_sk24
	s_add_u32 m0, s35, 0xc000
	s_nop 0
	global_load_lds_dwordx4 v234, s[26:27]
	s_add_u32 m0, s35, 0xe000
	s_nop 0
	global_load_lds_dwordx4 v235, s[26:27]
.Lwi_sk24:
	ds_read_b128 v[144:147], v207 offset:5120
	s_waitcnt lgkmcnt(2)
	s_setprio 1
	v_mfma_f32_16x16x32_bf16 v[124:127], v[160:163], v[128:131], v[124:127]
	v_mfma_f32_16x16x32_bf16 v[120:123], v[160:163], v[132:135], v[120:123]
	v_mfma_f32_16x16x32_bf16 v[116:119], v[160:163], v[136:139], v[116:119]
	v_mfma_f32_16x16x32_bf16 v[112:115], v[160:163], v[140:143], v[112:115]
	s_setprio 0
	ds_read_b128 v[148:151], v207 offset:7168
	s_waitcnt lgkmcnt(2)
	s_setprio 1
	v_mfma_f32_16x16x32_bf16 v[108:111], v[164:167], v[128:131], v[108:111]
	v_mfma_f32_16x16x32_bf16 v[104:107], v[164:167], v[132:135], v[104:107]
	v_mfma_f32_16x16x32_bf16 v[100:103], v[164:167], v[136:139], v[100:103]
	v_mfma_f32_16x16x32_bf16 v[96:99], v[164:167], v[140:143], v[96:99]
	s_setprio 0
	ds_read_b128 v[152:155], v207 offset:9216
	s_waitcnt lgkmcnt(2)
	s_setprio 1
	v_mfma_f32_16x16x32_bf16 v[92:95], v[144:147], v[128:131], v[92:95]
	v_mfma_f32_16x16x32_bf16 v[88:91], v[144:147], v[132:135], v[88:91]
	v_mfma_f32_16x16x32_bf16 v[84:87], v[144:147], v[136:139], v[84:87]
	v_mfma_f32_16x16x32_bf16 v[80:83], v[144:147], v[140:143], v[80:83]
	s_setprio 0
	ds_read_b128 v[144:147], v207 offset:11264
	s_waitcnt lgkmcnt(2)
	s_setprio 1
	v_mfma_f32_16x16x32_bf16 v[76:79], v[148:151], v[128:131], v[76:79]
	v_mfma_f32_16x16x32_bf16 v[72:75], v[148:151], v[132:135], v[72:75]
	v_mfma_f32_16x16x32_bf16 v[68:71], v[148:151], v[136:139], v[68:71]
	v_mfma_f32_16x16x32_bf16 v[64:67], v[148:151], v[140:143], v[64:67]
	s_setprio 0
	ds_read_b128 v[148:151], v207 offset:13312
	s_waitcnt lgkmcnt(2)
	s_setprio 1
	v_mfma_f32_16x16x32_bf16 v[60:63], v[152:155], v[128:131], v[60:63]
	v_mfma_f32_16x16x32_bf16 v[56:59], v[152:155], v[132:135], v[56:59]
	v_mfma_f32_16x16x32_bf16 v[52:55], v[152:155], v[136:139], v[52:55]
	v_mfma_f32_16x16x32_bf16 v[48:51], v[152:155], v[140:143], v[48:51]
	s_setprio 0
	ds_read_b128 v[152:155], v207 offset:15360
	s_waitcnt lgkmcnt(2)
	s_setprio 1
	v_mfma_f32_16x16x32_bf16 v[44:47], v[144:147], v[128:131], v[44:47]
	v_mfma_f32_16x16x32_bf16 v[40:43], v[144:147], v[132:135], v[40:43]
	v_mfma_f32_16x16x32_bf16 v[36:39], v[144:147], v[136:139], v[36:39]
	v_mfma_f32_16x16x32_bf16 v[32:35], v[144:147], v[140:143], v[32:35]
	s_setprio 0
	s_waitcnt vmcnt(0) lgkmcnt(0)
	s_barrier
	v_xor_b32_e32 v209, 0x10000, v209
	v_xor_b32_e32 v207, 0x10000, v207
	ds_read_b128 v[212:215], v209 offset:0
	ds_read_b128 v[216:219], v209 offset:2048
	ds_read_b128 v[220:223], v209 offset:4096
	ds_read_b128 v[224:227], v209 offset:6144
	ds_read_b128 v[228:231], v207 offset:0
	ds_read_b128 v[168:171], v207 offset:2048
	ds_read_b128 v[160:163], v207 offset:4096
	s_add_u32 s30, s30, 0x80
	s_addc_u32 s31, s31, 0
	s_add_u32 s17, s17, 0x80
	s_addc_u32 s19, s19, 0
	s_xor_b32 s35, s35, 0x10000
	s_add_i32 s34, s34, 1
	s_cmp_lg_u32 s34, -1
	s_cselect_b32 s28, s30, s22
	s_cselect_b32 s29, s31, s23
	s_cselect_b32 s26, s17, s24
	s_cselect_b32 s27, s19, s25
	s_cselect_b64 vcc, -1, s[20:21]
	s_cmp_eq_u32 s34, 0
	s_cselect_b64 vcc, 0, vcc
	s_setprio 1
	v_mfma_f32_16x16x32_bf16 v[28:31], v[148:151], v[128:131], v[28:31]
	v_mfma_f32_16x16x32_bf16 v[24:27], v[148:151], v[132:135], v[24:27]
	v_mfma_f32_16x16x32_bf16 v[20:23], v[148:151], v[136:139], v[20:23]
	v_mfma_f32_16x16x32_bf16 v[16:19], v[148:151], v[140:143], v[16:19]
	s_setprio 0
	s_setprio 1
	v_mfma_f32_16x16x32_bf16 v[12:15], v[152:155], v[128:131], v[12:15]
	v_mfma_f32_16x16x32_bf16 v[8:11], v[152:155], v[132:135], v[8:11]
	v_mfma_f32_16x16x32_bf16 v[4:7], v[152:155], v[136:139], v[4:7]
	v_mfma_f32_16x16x32_bf16 v[0:3], v[152:155], v[140:143], v[0:3]
	s_setprio 0
	s_cmp_lg_u32 s34, 0
	s_cbranch_scc1 .Lwi_head
	s_waitcnt lgkmcnt(0)
	s_branch .LBB0_854

; #define WAIT_V(n) asm volatile("s_waitcnt vmcnt(%0)" ::"n"(n) : "memory")
; #define DSR(dst, addr, OFF) asm volatile("ds_read_b128 %0, %1 offset:%2" : "=&v"(dst) : "v"(addr), "i"(OFF) : "memory")
; template <int EPI>
; __device__ __forceinline__ void gemm_phase(const Params& p, const u16* __restrict__ A, const u16* __restrict__ Bt, int K, int nN,
;                            u16* __restrict__ Cout, int ldc) {
;     ...
;     f32x4 acc[8][4];
; #pragma unroll
;     for (int m = 0; m < 8; ++m)
; #pragma unroll
;       for (int n = 0; n < 4; ++n) acc[m][n] = f32x4{0.f, 0.f, 0.f, 0.f};
;     if (!prefetched) {
; #pragma unroll
;       for (int i = 0; i < 8; ++i) GLDS_PIECE(i, Ab, Bb, 0);
;       WAIT_V(0); __syncthreads();
;     }
;     prefetched = has_next;
;     for (int t = 0; t < nt; ++t) {
;       const int cur = t & 1, nb = cur ^ 1;
;       const bool last = (t + 1 == nt);
;       const bool dostage = !last || has_next;
;       const u16* pa = last ? Abn : Ab + (t + 1) * BK;
;       const u16* pb = last ? Bbn : Bb + (t + 1) * BK;
;       bf16x8 Ar[3], Bq[2][4];
;       const unsigned la_u = lds0 + (unsigned)(cur * STAGE_B + aoff), lb_u = lds0 + (unsigned)(cur * STAGE_B + boff);
;     ...
;       DSR(Bq[0][0], lb_u, 0); DSR(Bq[0][1], lb_u, 2048); DSR(Bq[0][2], lb_u, 4096); DSR(Bq[0][3], lb_u, 6144);
;       DSR(Ar[0], la_u, 0); DSR(Ar[1], la_u, 2048);
;     ...
;       GSTEP(0, 2); GSTEP(1, 6); GSTEP(2, 6); GSTEP(3, 6); GSTEP(4, 2); GSTEP(5, 2); GSTEP(6, 2); GSTEP(7, 2);
;       GSTEP(8, 2); GSTEP(9, 2); GSTEP(10, 2); GSTEP(11, 2); GSTEP(12, 2); GSTEP(13, 2); GSTEP(14, 1); GSTEP(15, 0);
.LBB0_1104:
	s_mul_i32 s1, s24, s28
	s_mul_hi_i32 s0, s24, s28
	s_add_u32 s14, s22, s1
	s_addc_u32 s15, s23, s0
	s_mul_i32 s1, s24, s27
	s_mul_hi_i32 s0, s24, s27
	s_add_u32 s16, s25, s1
	v_mov_b32_e32 v0, 0
	s_addc_u32 s17, s26, s0
	s_mov_b32 s29, 0
	s_mov_b64 s[0:1], 0
	s_mov_b32 s30, 0
	v_mov_b32_e32 v1, v0
	v_mov_b32_e32 v2, v0
	v_mov_b32_e32 v3, v0
	v_mov_b32_e32 v4, v0
	v_mov_b32_e32 v5, v0
	v_mov_b32_e32 v6, v0
	v_mov_b32_e32 v7, v0
	v_mov_b32_e32 v8, v0
	v_mov_b32_e32 v9, v0
	v_mov_b32_e32 v10, v0
	v_mov_b32_e32 v11, v0
	v_mov_b32_e32 v12, v0
	v_mov_b32_e32 v13, v0
	v_mov_b32_e32 v14, v0
	v_mov_b32_e32 v15, v0
	v_mov_b32_e32 v16, v0
	v_mov_b32_e32 v17, v0
	v_mov_b32_e32 v18, v0
	v_mov_b32_e32 v19, v0
	v_mov_b32_e32 v20, v0
	v_mov_b32_e32 v21, v0
	v_mov_b32_e32 v22, v0
	v_mov_b32_e32 v23, v0
	v_mov_b32_e32 v24, v0
	v_mov_b32_e32 v25, v0
	v_mov_b32_e32 v26, v0
	v_mov_b32_e32 v27, v0
	v_mov_b32_e32 v28, v0
	v_mov_b32_e32 v29, v0
	v_mov_b32_e32 v30, v0
	v_mov_b32_e32 v31, v0
	v_mov_b32_e32 v32, v0
	v_mov_b32_e32 v33, v0
	v_mov_b32_e32 v34, v0
	v_mov_b32_e32 v35, v0
	v_mov_b32_e32 v36, v0
	v_mov_b32_e32 v37, v0
	v_mov_b32_e32 v38, v0
	v_mov_b32_e32 v39, v0
	v_mov_b32_e32 v40, v0
	v_mov_b32_e32 v41, v0
	v_mov_b32_e32 v42, v0
	v_mov_b32_e32 v43, v0
	v_mov_b32_e32 v44, v0
	v_mov_b32_e32 v45, v0
	v_mov_b32_e32 v46, v0
	v_mov_b32_e32 v47, v0
	v_mov_b32_e32 v48, v0
	v_mov_b32_e32 v49, v0
	v_mov_b32_e32 v50, v0
	v_mov_b32_e32 v51, v0
	v_mov_b32_e32 v52, v0
	v_mov_b32_e32 v53, v0
	v_mov_b32_e32 v54, v0
	v_mov_b32_e32 v55, v0
	v_mov_b32_e32 v56, v0
	v_mov_b32_e32 v57, v0
	v_mov_b32_e32 v58, v0
	v_mov_b32_e32 v59, v0
	v_mov_b32_e32 v60, v0
	v_mov_b32_e32 v61, v0
	v_mov_b32_e32 v62, v0
	v_mov_b32_e32 v63, v0
	v_mov_b32_e32 v64, v0
	v_mov_b32_e32 v65, v0
	v_mov_b32_e32 v66, v0
	v_mov_b32_e32 v67, v0
	v_mov_b32_e32 v68, v0
	v_mov_b32_e32 v69, v0
	v_mov_b32_e32 v70, v0
	v_mov_b32_e32 v71, v0
	v_mov_b32_e32 v72, v0
	v_mov_b32_e32 v73, v0
	v_mov_b32_e32 v74, v0
	v_mov_b32_e32 v75, v0
	v_mov_b32_e32 v76, v0
	v_mov_b32_e32 v77, v0
	v_mov_b32_e32 v78, v0
	v_mov_b32_e32 v79, v0
	v_mov_b32_e32 v80, v0
	v_mov_b32_e32 v81, v0
	v_mov_b32_e32 v82, v0
	v_mov_b32_e32 v83, v0
	v_mov_b32_e32 v84, v0
	v_mov_b32_e32 v85, v0
	v_mov_b32_e32 v86, v0
	v_mov_b32_e32 v87, v0
	v_mov_b32_e32 v88, v0
	v_mov_b32_e32 v89, v0
	v_mov_b32_e32 v90, v0
	v_mov_b32_e32 v91, v0
	v_mov_b32_e32 v92, v0
	v_mov_b32_e32 v93, v0
	v_mov_b32_e32 v94, v0
	v_mov_b32_e32 v95, v0
	v_mov_b32_e32 v96, v0
	v_mov_b32_e32 v97, v0
	v_mov_b32_e32 v98, v0
	v_mov_b32_e32 v99, v0
	v_mov_b32_e32 v100, v0
	v_mov_b32_e32 v101, v0
	v_mov_b32_e32 v102, v0
	v_mov_b32_e32 v103, v0
	v_mov_b32_e32 v104, v0
	v_mov_b32_e32 v105, v0
	v_mov_b32_e32 v106, v0
	v_mov_b32_e32 v107, v0
	v_mov_b32_e32 v108, v0
	v_mov_b32_e32 v109, v0
	v_mov_b32_e32 v110, v0
	v_mov_b32_e32 v111, v0
	v_mov_b32_e32 v112, v0
	v_mov_b32_e32 v113, v0
	v_mov_b32_e32 v114, v0
	v_mov_b32_e32 v115, v0
	v_mov_b32_e32 v116, v0
	v_mov_b32_e32 v117, v0
	v_mov_b32_e32 v118, v0
	v_mov_b32_e32 v119, v0
	v_mov_b32_e32 v120, v0
	v_mov_b32_e32 v121, v0
	v_mov_b32_e32 v122, v0
	v_mov_b32_e32 v123, v0
	v_mov_b32_e32 v124, v0
	v_mov_b32_e32 v125, v0
	v_mov_b32_e32 v126, v0
	v_mov_b32_e32 v127, v0
	s_not_b32 s30, s21
	s_mov_b64 s[34:35], s[16:17]
	s_mov_b64 s[0:1], s[14:15]
	v_mov_b32_e32 v198, v194
	v_mov_b32_e32 v197, v193
	ds_read_b128 v[212:215], v198 offset:0
	ds_read_b128 v[216:219], v198 offset:2048
	ds_read_b128 v[220:223], v198 offset:4096
	ds_read_b128 v[224:227], v198 offset:6144
	ds_read_b128 v[228:231], v197 offset:0
	ds_read_b128 v[168:171], v197 offset:2048
	ds_read_b128 v[160:163], v197 offset:4096
	v_readfirstlane_b32 s29, v192
	s_add_u32 s29, s29, 0x10000
	v_lshlrev_b32_e32 v232, 1, v174
	v_lshlrev_b32_e32 v233, 1, v176
	v_lshlrev_b32_e32 v234, 1, v178
	v_lshlrev_b32_e32 v235, 1, v180
	s_cmp_lg_u32 s30, -1
	s_cselect_b32 s34, s34, s10
	s_cselect_b32 s35, s35, s11
	s_cselect_b32 s0, s0, s6
	s_cselect_b32 s1, s1, s7
	s_cselect_b64 vcc, -1, s[12:13]
	v_readfirstlane_b32 s31, v192
	s_lshr_b32 s31, s31, 12
.Lss_head:
	s_waitcnt lgkmcnt(2)
	s_setprio 1
	v_mfma_f32_16x16x32_bf16 v[124:127], v[228:231], v[212:215], v[124:127]
	v_mfma_f32_16x16x32_bf16 v[120:123], v[228:231], v[216:219], v[120:123]
	v_mfma_f32_16x16x32_bf16 v[116:119], v[228:231], v[220:223], v[116:119]
	v_mfma_f32_16x16x32_bf16 v[112:115], v[228:231], v[224:227], v[112:115]
	s_setprio 0
	s_cbranch_vccz .Lss_sk1
	s_cmp_eq_u32 s31, 0
	s_cbranch_scc0 .Lss_sk1
	s_mov_b32 m0, s29
	s_nop 0
	global_load_lds_dwordx4 v232, s[34:35]
	s_add_u32 m0, s29, 0x2000
	s_nop 0
	global_load_lds_dwordx4 v233, s[34:35]
.Lss_sk1:
	ds_read_b128 v[164:167], v197 offset:6144
	ds_read_b128 v[128:131], v198 offset:1024
	ds_read_b128 v[132:135], v198 offset:3072
	ds_read_b128 v[136:139], v198 offset:5120
	ds_read_b128 v[140:143], v198 offset:7168
	s_waitcnt lgkmcnt(6)
	s_setprio 1
	v_mfma_f32_16x16x32_bf16 v[108:111], v[168:171], v[212:215], v[108:111]
	v_mfma_f32_16x16x32_bf16 v[104:107], v[168:171], v[216:219], v[104:107]
	v_mfma_f32_16x16x32_bf16 v[100:103], v[168:171], v[220:223], v[100:103]
	v_mfma_f32_16x16x32_bf16 v[96:99], v[168:171], v[224:227], v[96:99]
	s_setprio 0
	s_cbranch_vccz .Lss_sk2
	s_cmp_eq_u32 s31, 0
	s_cbranch_scc0 .Lss_sk2
	s_add_u32 m0, s29, 0x4000
	s_nop 0
	global_load_lds_dwordx4 v234, s[34:35]
	s_add_u32 m0, s29, 0x6000
	s_nop 0
	global_load_lds_dwordx4 v235, s[34:35]
; template <int EPI>
; __device__ __forceinline__ void gemm_phase(const Params& p, const u16* __restrict__ A, const u16* __restrict__ Bt, int K, int nN,
;                            u16* __restrict__ Cout, int ldc) {
;     ...
;       GSTEP(0, 2); GSTEP(1, 6); GSTEP(2, 6); GSTEP(3, 6); GSTEP(4, 2); GSTEP(5, 2); GSTEP(6, 2); GSTEP(7, 2);
;       GSTEP(8, 2); GSTEP(9, 2); GSTEP(10, 2); GSTEP(11, 2); GSTEP(12, 2); GSTEP(13, 2); GSTEP(14, 1); GSTEP(15, 0);
.Lss_sk2:
	ds_read_b128 v[168:171], v197 offset:8192
	s_waitcnt lgkmcnt(6)
	s_setprio 1
	v_mfma_f32_16x16x32_bf16 v[92:95], v[160:163], v[212:215], v[92:95]
	v_mfma_f32_16x16x32_bf16 v[88:91], v[160:163], v[216:219], v[88:91]
	v_mfma_f32_16x16x32_bf16 v[84:87], v[160:163], v[220:223], v[84:87]
	v_mfma_f32_16x16x32_bf16 v[80:83], v[160:163], v[224:227], v[80:83]
	s_setprio 0
	s_cbranch_vccz .Lss_sk3
	s_cmp_eq_u32 s31, 0
	s_cbranch_scc0 .Lss_sk3
	s_add_u32 m0, s29, 0x8000
	s_nop 0
	global_load_lds_dwordx4 v232, s[0:1]
	s_add_u32 m0, s29, 0xa000
	s_nop 0
	global_load_lds_dwordx4 v233, s[0:1]
.Lss_sk3:
	ds_read_b128 v[160:163], v197 offset:10240
	s_waitcnt lgkmcnt(6)
	s_setprio 1
	v_mfma_f32_16x16x32_bf16 v[76:79], v[164:167], v[212:215], v[76:79]
	v_mfma_f32_16x16x32_bf16 v[72:75], v[164:167], v[216:219], v[72:75]
	v_mfma_f32_16x16x32_bf16 v[68:71], v[164:167], v[220:223], v[68:71]
	v_mfma_f32_16x16x32_bf16 v[64:67], v[164:167], v[224:227], v[64:67]
	s_setprio 0
	s_cbranch_vccz .Lss_sk4
	s_cmp_eq_u32 s31, 0
	s_cbranch_scc0 .Lss_sk4
	s_add_u32 m0, s29, 0xc000
	s_nop 0
	global_load_lds_dwordx4 v234, s[0:1]
	s_add_u32 m0, s29, 0xe000
	s_nop 0
	global_load_lds_dwordx4 v235, s[0:1]
.Lss_sk4:
	ds_read_b128 v[164:167], v197 offset:12288
	s_waitcnt lgkmcnt(2)
	s_setprio 1
	v_mfma_f32_16x16x32_bf16 v[60:63], v[168:171], v[212:215], v[60:63]
	v_mfma_f32_16x16x32_bf16 v[56:59], v[168:171], v[216:219], v[56:59]
	v_mfma_f32_16x16x32_bf16 v[52:55], v[168:171], v[220:223], v[52:55]
	v_mfma_f32_16x16x32_bf16 v[48:51], v[168:171], v[224:227], v[48:51]
	s_setprio 0
	s_cbranch_vccz .Lss_sk5
	s_cmp_eq_u32 s31, 1
	s_cbranch_scc0 .Lss_sk5
	s_mov_b32 m0, s29
	s_nop 0
	global_load_lds_dwordx4 v232, s[34:35]
	s_add_u32 m0, s29, 0x2000
	s_nop 0
	global_load_lds_dwordx4 v233, s[34:35]
.Lss_sk5:
	ds_read_b128 v[168:171], v197 offset:14336
	s_waitcnt lgkmcnt(2)
	s_setprio 1
	v_mfma_f32_16x16x32_bf16 v[44:47], v[160:163], v[212:215], v[44:47]
	v_mfma_f32_16x16x32_bf16 v[40:43], v[160:163], v[216:219], v[40:43]
	v_mfma_f32_16x16x32_bf16 v[36:39], v[160:163], v[220:223], v[36:39]
	v_mfma_f32_16x16x32_bf16 v[32:35], v[160:163], v[224:227], v[32:35]
	s_setprio 0
	s_cbranch_vccz .Lss_sk6
	s_cmp_eq_u32 s31, 1
	s_cbranch_scc0 .Lss_sk6
	s_add_u32 m0, s29, 0x4000
	s_nop 0
	global_load_lds_dwordx4 v234, s[34:35]
	s_add_u32 m0, s29, 0x6000
	s_nop 0
	global_load_lds_dwordx4 v235, s[34:35]
.Lss_sk6:
	ds_read_b128 v[160:163], v197 offset:1024
	s_waitcnt lgkmcnt(2)
	s_setprio 1
	v_mfma_f32_16x16x32_bf16 v[28:31], v[164:167], v[212:215], v[28:31]
	v_mfma_f32_16x16x32_bf16 v[24:27], v[164:167], v[216:219], v[24:27]
	v_mfma_f32_16x16x32_bf16 v[20:23], v[164:167], v[220:223], v[20:23]
	v_mfma_f32_16x16x32_bf16 v[16:19], v[164:167], v[224:227], v[16:19]
	s_setprio 0
	s_cbranch_vccz .Lss_sk7
	s_cmp_eq_u32 s31, 1
	s_cbranch_scc0 .Lss_sk7
	s_add_u32 m0, s29, 0x8000
	s_nop 0
	global_load_lds_dwordx4 v232, s[0:1]
	s_add_u32 m0, s29, 0xa000
	s_nop 0
	global_load_lds_dwordx4 v233, s[0:1]
.Lss_sk7:
	ds_read_b128 v[164:167], v197 offset:3072
	s_waitcnt lgkmcnt(2)
	s_setprio 1
	v_mfma_f32_16x16x32_bf16 v[12:15], v[168:171], v[212:215], v[12:15]
	v_mfma_f32_16x16x32_bf16 v[8:11], v[168:171], v[216:219], v[8:11]
	v_mfma_f32_16x16x32_bf16 v[4:7], v[168:171], v[220:223], v[4:7]
	v_mfma_f32_16x16x32_bf16 v[0:3], v[168:171], v[224:227], v[0:3]
	s_setprio 0
	s_cbranch_vccz .Lss_sk8
	s_cmp_eq_u32 s31, 1
	s_cbranch_scc0 .Lss_sk8
	s_add_u32 m0, s29, 0xc000
	s_nop 0
	global_load_lds_dwordx4 v234, s[0:1]
	s_add_u32 m0, s29, 0xe000
	s_nop 0
	global_load_lds_dwordx4 v235, s[0:1]
; __device__ __forceinline__ float rsq_(float x) { return __builtin_amdgcn_rsqf(x); }
; #define WAIT_V(n) asm volatile("s_waitcnt vmcnt(%0)" ::"n"(n) : "memory")
; template <int EPI>
; __device__ __forceinline__ void gemm_phase(const Params& p, const u16* __restrict__ A, const u16* __restrict__ Bt, int K, int nN,
;                            u16* __restrict__ Cout, int ldc) {
;     ...
;       GSTEP(0, 2); GSTEP(1, 6); GSTEP(2, 6); GSTEP(3, 6); GSTEP(4, 2); GSTEP(5, 2); GSTEP(6, 2); GSTEP(7, 2);
;       GSTEP(8, 2); GSTEP(9, 2); GSTEP(10, 2); GSTEP(11, 2); GSTEP(12, 2); GSTEP(13, 2); GSTEP(14, 1); GSTEP(15, 0);
;       WAIT_V(0);
;       if (EPI != EPI_SS && t == 0 && tid < 256) rsl[tid] = rsq_(ssv * (1.f / DM) + EPS);
;       __syncthreads();
;     }
.Lss_sk8:
	ds_read_b128 v[144:147], v197 offset:5120
	s_waitcnt lgkmcnt(2)
	s_setprio 1
	v_mfma_f32_16x16x32_bf16 v[124:127], v[160:163], v[128:131], v[124:127]
	v_mfma_f32_16x16x32_bf16 v[120:123], v[160:163], v[132:135], v[120:123]
	v_mfma_f32_16x16x32_bf16 v[116:119], v[160:163], v[136:139], v[116:119]
	v_mfma_f32_16x16x32_bf16 v[112:115], v[160:163], v[140:143], v[112:115]
	s_setprio 0
	ds_read_b128 v[148:151], v197 offset:7168
	s_waitcnt lgkmcnt(2)
	s_setprio 1
	v_mfma_f32_16x16x32_bf16 v[108:111], v[164:167], v[128:131], v[108:111]
	v_mfma_f32_16x16x32_bf16 v[104:107], v[164:167], v[132:135], v[104:107]
	v_mfma_f32_16x16x32_bf16 v[100:103], v[164:167], v[136:139], v[100:103]
	v_mfma_f32_16x16x32_bf16 v[96:99], v[164:167], v[140:143], v[96:99]
	s_setprio 0
	ds_read_b128 v[152:155], v197 offset:9216
	s_waitcnt lgkmcnt(2)
	s_setprio 1
	v_mfma_f32_16x16x32_bf16 v[92:95], v[144:147], v[128:131], v[92:95]
	v_mfma_f32_16x16x32_bf16 v[88:91], v[144:147], v[132:135], v[88:91]
	v_mfma_f32_16x16x32_bf16 v[84:87], v[144:147], v[136:139], v[84:87]
	v_mfma_f32_16x16x32_bf16 v[80:83], v[144:147], v[140:143], v[80:83]
	s_setprio 0
	ds_read_b128 v[144:147], v197 offset:11264
	s_waitcnt lgkmcnt(2)
	s_setprio 1
	v_mfma_f32_16x16x32_bf16 v[76:79], v[148:151], v[128:131], v[76:79]
	v_mfma_f32_16x16x32_bf16 v[72:75], v[148:151], v[132:135], v[72:75]
	v_mfma_f32_16x16x32_bf16 v[68:71], v[148:151], v[136:139], v[68:71]
	v_mfma_f32_16x16x32_bf16 v[64:67], v[148:151], v[140:143], v[64:67]
	s_setprio 0
	ds_read_b128 v[148:151], v197 offset:13312
	s_waitcnt lgkmcnt(2)
	s_setprio 1
	v_mfma_f32_16x16x32_bf16 v[60:63], v[152:155], v[128:131], v[60:63]
	v_mfma_f32_16x16x32_bf16 v[56:59], v[152:155], v[132:135], v[56:59]
	v_mfma_f32_16x16x32_bf16 v[52:55], v[152:155], v[136:139], v[52:55]
	v_mfma_f32_16x16x32_bf16 v[48:51], v[152:155], v[140:143], v[48:51]
	s_setprio 0
	ds_read_b128 v[152:155], v197 offset:15360
	s_waitcnt lgkmcnt(2)
	s_setprio 1
	v_mfma_f32_16x16x32_bf16 v[44:47], v[144:147], v[128:131], v[44:47]
	v_mfma_f32_16x16x32_bf16 v[40:43], v[144:147], v[132:135], v[40:43]
	v_mfma_f32_16x16x32_bf16 v[36:39], v[144:147], v[136:139], v[36:39]
	v_mfma_f32_16x16x32_bf16 v[32:35], v[144:147], v[140:143], v[32:35]
	s_setprio 0
	s_waitcnt vmcnt(0) lgkmcnt(0)
	s_barrier
	v_xor_b32_e32 v198, 0x10000, v198
	v_xor_b32_e32 v197, 0x10000, v197
	ds_read_b128 v[212:215], v198 offset:0
	ds_read_b128 v[216:219], v198 offset:2048
	ds_read_b128 v[220:223], v198 offset:4096
	ds_read_b128 v[224:227], v198 offset:6144
	ds_read_b128 v[228:231], v197 offset:0
	ds_read_b128 v[168:171], v197 offset:2048
	ds_read_b128 v[160:163], v197 offset:4096
	s_add_u32 s34, s34, 0x80
	s_addc_u32 s35, s35, 0
	s_add_u32 s0, s0, 0x80
	s_addc_u32 s1, s1, 0
	s_xor_b32 s29, s29, 0x10000
	s_add_i32 s30, s30, 1
	s_cmp_lg_u32 s30, -1
	s_cselect_b32 s34, s34, s10
	s_cselect_b32 s35, s35, s11
	s_cselect_b32 s0, s0, s6
	s_cselect_b32 s1, s1, s7
	s_cselect_b64 vcc, -1, s[12:13]
	s_cmp_eq_u32 s30, 0
	s_cselect_b64 vcc, 0, vcc
	s_setprio 1
	v_mfma_f32_16x16x32_bf16 v[28:31], v[148:151], v[128:131], v[28:31]
	v_mfma_f32_16x16x32_bf16 v[24:27], v[148:151], v[132:135], v[24:27]
	v_mfma_f32_16x16x32_bf16 v[20:23], v[148:151], v[136:139], v[20:23]
	v_mfma_f32_16x16x32_bf16 v[16:19], v[148:151], v[140:143], v[16:19]
	s_setprio 0
	s_setprio 1
	v_mfma_f32_16x16x32_bf16 v[12:15], v[152:155], v[128:131], v[12:15]
	v_mfma_f32_16x16x32_bf16 v[8:11], v[152:155], v[132:135], v[8:11]
	v_mfma_f32_16x16x32_bf16 v[4:7], v[152:155], v[136:139], v[4:7]
	v_mfma_f32_16x16x32_bf16 v[0:3], v[152:155], v[140:143], v[0:3]
	s_setprio 0
	s_cmp_lg_u32 s30, 0
	s_cbranch_scc1 .Lss_head
	s_waitcnt lgkmcnt(0)
	v_mov_b32_e32 v128, v124
	v_mov_b32_e32 v129, v125
	v_mov_b32_e32 v130, v126
	v_mov_b32_e32 v131, v127
	v_mov_b32_e32 v132, v120
	v_mov_b32_e32 v133, v121
	v_mov_b32_e32 v134, v122
	v_mov_b32_e32 v135, v123
	v_mov_b32_e32 v136, v116
	v_mov_b32_e32 v137, v117
	v_mov_b32_e32 v138, v118
	v_mov_b32_e32 v139, v119
	v_mov_b32_e32 v140, v112
	v_mov_b32_e32 v141, v113
	v_mov_b32_e32 v142, v114
	v_mov_b32_e32 v143, v115
	v_mov_b32_e32 v148, v64
	v_mov_b32_e32 v149, v65
	v_mov_b32_e32 v150, v66
	v_mov_b32_e32 v151, v67
	s_branch .Lss_epi

; #define DSR(dst, addr, OFF) asm volatile("ds_read_b128 %0, %1 offset:%2" : "=&v"(dst) : "v"(addr), "i"(OFF) : "memory")
; template <int EPI>
; __device__ __forceinline__ void gemm_phase(const Params& p, const u16* __restrict__ A, const u16* __restrict__ Bt, int K, int nN,
;                            u16* __restrict__ Cout, int ldc) {
;     ...
;     for (int t = 0; t < nt; ++t) {
;       const int cur = t & 1, nb = cur ^ 1;
;       const bool last = (t + 1 == nt);
;       const bool dostage = !last || has_next;
;       const u16* pa = last ? Abn : Ab + (t + 1) * BK;
;       const u16* pb = last ? Bbn : Bb + (t + 1) * BK;
;       bf16x8 Ar[3], Bq[2][4];
;       const unsigned la_u = lds0 + (unsigned)(cur * STAGE_B + aoff), lb_u = lds0 + (unsigned)(cur * STAGE_B + boff);
;     ...
;       DSR(Bq[0][0], lb_u, 0); DSR(Bq[0][1], lb_u, 2048); DSR(Bq[0][2], lb_u, 4096); DSR(Bq[0][3], lb_u, 6144);
;       DSR(Ar[0], la_u, 0); DSR(Ar[1], la_u, 2048);
;     ...
;       GSTEP(0, 2); GSTEP(1, 6); GSTEP(2, 6); GSTEP(3, 6); GSTEP(4, 2); GSTEP(5, 2); GSTEP(6, 2); GSTEP(7, 2);
;       GSTEP(8, 2); GSTEP(9, 2); GSTEP(10, 2); GSTEP(11, 2); GSTEP(12, 2); GSTEP(13, 2); GSTEP(14, 1); GSTEP(15, 0);
.LBB0_1131:
	ds_read_b128 v[0:3], v194 offset:0
	ds_read_b128 v[4:7], v194 offset:0x800
	ds_read_b128 v[8:11], v194 offset:0x1000
	ds_read_b128 v[12:15], v194 offset:0x1800
	ds_read_b128 v[16:19], v193 offset:0
	ds_read_b128 v[20:23], v193 offset:0x800
	ds_read_b128 v[24:27], v193 offset:0x1000
	s_waitcnt lgkmcnt(2)
	s_setprio 1
	v_mfma_f32_16x16x32_bf16 v[28:31], v[16:19], v[0:3], 0
	v_mfma_f32_16x16x32_bf16 v[32:35], v[16:19], v[4:7], 0
	v_mfma_f32_16x16x32_bf16 v[36:39], v[16:19], v[8:11], 0
	v_mfma_f32_16x16x32_bf16 v[16:19], v[16:19], v[12:15], 0
	s_setprio 0
	v_mov_b32_e32 v40, v176
	v_mov_b32_e32 v41, v172
	v_lshl_add_u64 v[40:41], v[40:41], 1, s[24:25]
	v_readfirstlane_b32 s13, v198
	v_lshl_add_u64 v[40:41], v[40:41], 0, s[62:63]
	s_mov_b32 m0, s13
	s_nop 0
	global_load_lds_dwordx4 v[40:41], off
	ds_read_b128 v[40:43], v193 offset:0x1800
	ds_read_b128 v[130:133], v194 offset:0x400
	ds_read_b128 v[134:137], v194 offset:0xc00
	ds_read_b128 v[138:141], v194 offset:0x1400
	ds_read_b128 v[142:145], v194 offset:0x1c00
	s_waitcnt lgkmcnt(6)
	s_setprio 1
	v_mfma_f32_16x16x32_bf16 v[44:47], v[20:23], v[0:3], 0
	v_mfma_f32_16x16x32_bf16 v[48:51], v[20:23], v[4:7], 0
	v_mfma_f32_16x16x32_bf16 v[52:55], v[20:23], v[8:11], 0
	v_mfma_f32_16x16x32_bf16 v[20:23], v[20:23], v[12:15], 0
	s_setprio 0
	v_mov_b32_e32 v56, v178
	v_mov_b32_e32 v57, v172
	v_lshl_add_u64 v[56:57], v[56:57], 1, s[24:25]
	v_readfirstlane_b32 s13, v199
	v_lshl_add_u64 v[56:57], v[56:57], 0, s[62:63]
	s_mov_b32 m0, s13
	s_nop 0
	global_load_lds_dwordx4 v[56:57], off
	ds_read_b128 v[56:59], v193 offset:0x2000
	s_waitcnt lgkmcnt(6)
	s_setprio 1
	v_mfma_f32_16x16x32_bf16 v[60:63], v[24:27], v[0:3], 0
	v_mfma_f32_16x16x32_bf16 v[64:67], v[24:27], v[4:7], 0
	v_mfma_f32_16x16x32_bf16 v[68:71], v[24:27], v[8:11], 0
	v_mfma_f32_16x16x32_bf16 v[24:27], v[24:27], v[12:15], 0
	s_setprio 0
	v_mov_b32_e32 v72, v180
	v_mov_b32_e32 v73, v172
	v_lshl_add_u64 v[72:73], v[72:73], 1, s[24:25]
	v_readfirstlane_b32 s13, v200
	v_lshl_add_u64 v[72:73], v[72:73], 0, s[62:63]
	s_mov_b32 m0, s13
	s_nop 0
	global_load_lds_dwordx4 v[72:73], off
	ds_read_b128 v[72:75], v193 offset:0x2800
	s_waitcnt lgkmcnt(6)
	s_setprio 1
	v_mfma_f32_16x16x32_bf16 v[76:79], v[40:43], v[0:3], 0
	v_mfma_f32_16x16x32_bf16 v[146:149], v[40:43], v[4:7], 0
	v_mfma_f32_16x16x32_bf16 v[150:153], v[40:43], v[8:11], 0
	v_mfma_f32_16x16x32_bf16 v[40:43], v[40:43], v[12:15], 0
	s_setprio 0
	v_mov_b32_e32 v80, v191
	v_mov_b32_e32 v81, v172
	v_lshl_add_u64 v[80:81], v[80:81], 1, s[24:25]
	v_readfirstlane_b32 s13, v201
	v_lshl_add_u64 v[80:81], v[80:81], 0, s[62:63]
	s_mov_b32 m0, s13
	s_nop 0
	global_load_lds_dwordx4 v[80:81], off
	ds_read_b128 v[80:83], v193 offset:0x3000
	s_waitcnt lgkmcnt(2)
	s_setprio 1
	v_mfma_f32_16x16x32_bf16 v[154:157], v[56:59], v[0:3], 0
	v_mfma_f32_16x16x32_bf16 v[158:161], v[56:59], v[4:7], 0
	v_mfma_f32_16x16x32_bf16 v[162:165], v[56:59], v[8:11], 0
	v_mfma_f32_16x16x32_bf16 v[166:169], v[56:59], v[12:15], 0
	s_setprio 0
	v_mov_b32_e32 v56, v176
	v_mov_b32_e32 v57, v172
	v_lshl_add_u64 v[56:57], v[56:57], 1, s[22:23]
	v_readfirstlane_b32 s13, v205
	v_lshl_add_u64 v[56:57], v[56:57], 0, s[62:63]
	s_mov_b32 m0, s13
	s_nop 0
	global_load_lds_dwordx4 v[56:57], off
	ds_read_b128 v[56:59], v193 offset:0x3800
	s_waitcnt lgkmcnt(2)
	s_setprio 1
	v_mfma_f32_16x16x32_bf16 v[206:209], v[72:75], v[0:3], 0
	v_mfma_f32_16x16x32_bf16 v[210:213], v[72:75], v[4:7], 0
	v_mfma_f32_16x16x32_bf16 v[214:217], v[72:75], v[8:11], 0
	v_mfma_f32_16x16x32_bf16 v[218:221], v[72:75], v[12:15], 0
	s_setprio 0
	v_mov_b32_e32 v72, v178
	v_mov_b32_e32 v73, v172
	v_lshl_add_u64 v[72:73], v[72:73], 1, s[22:23]
	v_readfirstlane_b32 s13, v202
	v_lshl_add_u64 v[72:73], v[72:73], 0, s[62:63]
	s_mov_b32 m0, s13
	s_nop 0
	global_load_lds_dwordx4 v[72:73], off
	ds_read_b128 v[72:75], v193 offset:0x400
	s_waitcnt lgkmcnt(2)
	s_setprio 1
	v_mfma_f32_16x16x32_bf16 v[222:225], v[80:83], v[0:3], 0
	v_mfma_f32_16x16x32_bf16 v[226:229], v[80:83], v[4:7], 0
	v_mfma_f32_16x16x32_bf16 v[230:233], v[80:83], v[8:11], 0
	v_mfma_f32_16x16x32_bf16 v[234:237], v[80:83], v[12:15], 0
	s_setprio 0
	v_mov_b32_e32 v80, v180
	v_mov_b32_e32 v81, v172
	v_lshl_add_u64 v[80:81], v[80:81], 1, s[22:23]
	v_readfirstlane_b32 s13, v203
	v_lshl_add_u64 v[80:81], v[80:81], 0, s[62:63]
	s_mov_b32 m0, s13
	s_nop 0
	global_load_lds_dwordx4 v[80:81], off
	ds_read_b128 v[80:83], v193 offset:0xc00
	s_waitcnt lgkmcnt(2)
	s_setprio 1
	v_mfma_f32_16x16x32_bf16 v[0:3], v[56:59], v[0:3], 0
	v_mfma_f32_16x16x32_bf16 v[4:7], v[56:59], v[4:7], 0
	v_mfma_f32_16x16x32_bf16 v[238:241], v[56:59], v[8:11], 0
	v_mfma_f32_16x16x32_bf16 v[242:245], v[56:59], v[12:15], 0
	s_setprio 0
	v_mov_b32_e32 v8, v191
	v_mov_b32_e32 v9, v172
	v_lshl_add_u64 v[8:9], v[8:9], 1, s[22:23]
	v_readfirstlane_b32 s13, v204
	v_lshl_add_u64 v[8:9], v[8:9], 0, s[62:63]
	s_mov_b32 m0, s13
	s_nop 0
	global_load_lds_dwordx4 v[8:9], off
	ds_read_b128 v[8:11], v193 offset:0x1400
	s_waitcnt lgkmcnt(2)
	s_setprio 1
	v_mfma_f32_16x16x32_bf16 v[124:127], v[72:75], v[130:133], v[28:31]
	v_mfma_f32_16x16x32_bf16 v[120:123], v[72:75], v[134:137], v[32:35]
	v_mfma_f32_16x16x32_bf16 v[116:119], v[72:75], v[138:141], v[36:39]
	v_mfma_f32_16x16x32_bf16 v[112:115], v[72:75], v[142:145], v[16:19]
	s_setprio 0
	ds_read_b128 v[12:15], v193 offset:0x1c00
	s_waitcnt lgkmcnt(2)
	s_setprio 1
	v_mfma_f32_16x16x32_bf16 v[108:111], v[80:83], v[130:133], v[44:47]
	v_mfma_f32_16x16x32_bf16 v[104:107], v[80:83], v[134:137], v[48:51]
	v_mfma_f32_16x16x32_bf16 v[100:103], v[80:83], v[138:141], v[52:55]
	v_mfma_f32_16x16x32_bf16 v[96:99], v[80:83], v[142:145], v[20:23]
	s_setprio 0
	ds_read_b128 v[16:19], v193 offset:0x2400
	s_waitcnt lgkmcnt(2)
; __device__ __forceinline__ float rsq_(float x) { return __builtin_amdgcn_rsqf(x); }
; #define WAIT_V(n) asm volatile("s_waitcnt vmcnt(%0)" ::"n"(n) : "memory")
; #define DSR(dst, addr, OFF) asm volatile("ds_read_b128 %0, %1 offset:%2" : "=&v"(dst) : "v"(addr), "i"(OFF) : "memory")
; template <int EPI>
; __device__ __forceinline__ void gemm_phase(const Params& p, const u16* __restrict__ A, const u16* __restrict__ Bt, int K, int nN,
;                            u16* __restrict__ Cout, int ldc) {
;     ...
;     for (int t = 0; t < nt; ++t) {
;       const int cur = t & 1, nb = cur ^ 1;
;       const bool last = (t + 1 == nt);
;       const bool dostage = !last || has_next;
;       const u16* pa = last ? Abn : Ab + (t + 1) * BK;
;       const u16* pb = last ? Bbn : Bb + (t + 1) * BK;
;       bf16x8 Ar[3], Bq[2][4];
;       const unsigned la_u = lds0 + (unsigned)(cur * STAGE_B + aoff), lb_u = lds0 + (unsigned)(cur * STAGE_B + boff);
;     ...
;       DSR(Bq[0][0], lb_u, 0); DSR(Bq[0][1], lb_u, 2048); DSR(Bq[0][2], lb_u, 4096); DSR(Bq[0][3], lb_u, 6144);
;       DSR(Ar[0], la_u, 0); DSR(Ar[1], la_u, 2048);
;     ...
;       GSTEP(0, 2); GSTEP(1, 6); GSTEP(2, 6); GSTEP(3, 6); GSTEP(4, 2); GSTEP(5, 2); GSTEP(6, 2); GSTEP(7, 2);
;       GSTEP(8, 2); GSTEP(9, 2); GSTEP(10, 2); GSTEP(11, 2); GSTEP(12, 2); GSTEP(13, 2); GSTEP(14, 1); GSTEP(15, 0);
;       WAIT_V(0);
;       if (EPI != EPI_SS && t == 0 && tid < 256) rsl[tid] = rsq_(ssv * (1.f / DM) + EPS);
;       __syncthreads();
	s_setprio 1
	v_mfma_f32_16x16x32_bf16 v[92:95], v[8:11], v[130:133], v[60:63]
	v_mfma_f32_16x16x32_bf16 v[88:91], v[8:11], v[134:137], v[64:67]
	v_mfma_f32_16x16x32_bf16 v[84:87], v[8:11], v[138:141], v[68:71]
	v_mfma_f32_16x16x32_bf16 v[80:83], v[8:11], v[142:145], v[24:27]
	s_setprio 0
	ds_read_b128 v[8:11], v193 offset:0x2c00
	s_waitcnt lgkmcnt(2)
	s_setprio 1
	v_mfma_f32_16x16x32_bf16 v[76:79], v[12:15], v[130:133], v[76:79]
	v_mfma_f32_16x16x32_bf16 v[72:75], v[12:15], v[134:137], v[146:149]
	v_mfma_f32_16x16x32_bf16 v[68:71], v[12:15], v[138:141], v[150:153]
	v_mfma_f32_16x16x32_bf16 v[64:67], v[12:15], v[142:145], v[40:43]
	s_setprio 0
	ds_read_b128 v[12:15], v193 offset:0x3400
	s_waitcnt lgkmcnt(2)
	s_setprio 1
	v_mfma_f32_16x16x32_bf16 v[60:63], v[16:19], v[130:133], v[154:157]
	v_mfma_f32_16x16x32_bf16 v[56:59], v[16:19], v[134:137], v[158:161]
	v_mfma_f32_16x16x32_bf16 v[52:55], v[16:19], v[138:141], v[162:165]
	v_mfma_f32_16x16x32_bf16 v[48:51], v[16:19], v[142:145], v[166:169]
	s_setprio 0
	ds_read_b128 v[146:149], v193 offset:0x3c00
	s_waitcnt lgkmcnt(2)
	s_setprio 1
	v_mfma_f32_16x16x32_bf16 v[44:47], v[8:11], v[130:133], v[206:209]
	v_mfma_f32_16x16x32_bf16 v[40:43], v[8:11], v[134:137], v[210:213]
	v_mfma_f32_16x16x32_bf16 v[36:39], v[8:11], v[138:141], v[214:217]
	v_mfma_f32_16x16x32_bf16 v[32:35], v[8:11], v[142:145], v[218:221]
	s_setprio 0
	s_waitcnt lgkmcnt(1)
	s_setprio 1
	v_mfma_f32_16x16x32_bf16 v[28:31], v[12:15], v[130:133], v[222:225]
	v_mfma_f32_16x16x32_bf16 v[24:27], v[12:15], v[134:137], v[226:229]
	v_mfma_f32_16x16x32_bf16 v[20:23], v[12:15], v[138:141], v[230:233]
	v_mfma_f32_16x16x32_bf16 v[16:19], v[12:15], v[142:145], v[234:237]
	s_setprio 0
	s_waitcnt lgkmcnt(0)
	s_setprio 1
	v_mfma_f32_16x16x32_bf16 v[12:15], v[146:149], v[130:133], v[0:3]
	v_mfma_f32_16x16x32_bf16 v[8:11], v[146:149], v[134:137], v[4:7]
	v_mfma_f32_16x16x32_bf16 v[4:7], v[146:149], v[138:141], v[238:241]
	v_mfma_f32_16x16x32_bf16 v[0:3], v[146:149], v[142:145], v[242:245]
	s_setprio 0
	s_waitcnt vmcnt(0)
	s_and_saveexec_b64 s[22:23], s[0:1]
	v_rsq_f32_e32 v128, v128
	ds_write_b32 v195, v128
	s_or_b64 exec, exec, s[22:23]
	s_add_u32 s13, s35, s20
	s_addc_u32 s24, s36, s21
	s_add_u32 s25, s37, s2
	s_addc_u32 s26, s38, s3
	s_mov_b32 s27, -15
	s_waitcnt vmcnt(0) lgkmcnt(0)
	s_barrier
	v_or_b32_e32 v208, 0x10000, v194
	v_add_u32_e32 v206, 0x10000, v193
	ds_read_b128 v[212:215], v208 offset:0
	ds_read_b128 v[216:219], v208 offset:2048
	ds_read_b128 v[220:223], v208 offset:4096
	ds_read_b128 v[224:227], v208 offset:6144
	ds_read_b128 v[228:231], v206 offset:0
	ds_read_b128 v[168:171], v206 offset:2048
	ds_read_b128 v[160:163], v206 offset:4096
	v_readfirstlane_b32 s40, v175
	v_lshlrev_b32_e32 v232, 1, v176
	v_lshlrev_b32_e32 v233, 1, v178
	v_lshlrev_b32_e32 v234, 1, v180
	v_lshlrev_b32_e32 v235, 1, v191
	s_cmp_lg_u32 s27, -1
	s_cselect_b32 s22, s25, s16
	s_cselect_b32 s23, s26, s17
	s_cselect_b32 s20, s13, s18
	s_cselect_b32 s21, s24, s19
	s_cselect_b64 vcc, -1, s[10:11]
	v_readfirstlane_b32 s28, v175
	s_lshr_b32 s28, s28, 12
.Lgu_head:
	s_waitcnt lgkmcnt(2)
	s_setprio 1
	v_mfma_f32_16x16x32_bf16 v[124:127], v[228:231], v[212:215], v[124:127]
	v_mfma_f32_16x16x32_bf16 v[120:123], v[228:231], v[216:219], v[120:123]
	v_mfma_f32_16x16x32_bf16 v[116:119], v[228:231], v[220:223], v[116:119]
	v_mfma_f32_16x16x32_bf16 v[112:115], v[228:231], v[224:227], v[112:115]
	s_setprio 0
	s_cbranch_vccz .Lgu_sk9
	s_cmp_eq_u32 s28, 0
	s_cbranch_scc0 .Lgu_sk9
	s_mov_b32 m0, s40
	s_nop 0
	global_load_lds_dwordx4 v232, s[22:23]
	s_add_u32 m0, s40, 0x2000
	s_nop 0
	global_load_lds_dwordx4 v233, s[22:23]
.Lgu_sk9:
	ds_read_b128 v[164:167], v206 offset:6144
	ds_read_b128 v[128:131], v208 offset:1024
	ds_read_b128 v[132:135], v208 offset:3072
	ds_read_b128 v[136:139], v208 offset:5120
	ds_read_b128 v[140:143], v208 offset:7168
	s_waitcnt lgkmcnt(6)
	s_setprio 1
	v_mfma_f32_16x16x32_bf16 v[108:111], v[168:171], v[212:215], v[108:111]
	v_mfma_f32_16x16x32_bf16 v[104:107], v[168:171], v[216:219], v[104:107]
	v_mfma_f32_16x16x32_bf16 v[100:103], v[168:171], v[220:223], v[100:103]
	v_mfma_f32_16x16x32_bf16 v[96:99], v[168:171], v[224:227], v[96:99]
	s_setprio 0
	s_cbranch_vccz .Lgu_sk10
	s_cmp_eq_u32 s28, 0
	s_cbranch_scc0 .Lgu_sk10
	s_add_u32 m0, s40, 0x4000
	s_nop 0
	global_load_lds_dwordx4 v234, s[22:23]
	s_add_u32 m0, s40, 0x6000
	s_nop 0
	global_load_lds_dwordx4 v235, s[22:23]
.Lgu_sk10:
	ds_read_b128 v[168:171], v206 offset:8192
	s_waitcnt lgkmcnt(6)
	s_setprio 1
	v_mfma_f32_16x16x32_bf16 v[92:95], v[160:163], v[212:215], v[92:95]
	v_mfma_f32_16x16x32_bf16 v[88:91], v[160:163], v[216:219], v[88:91]
	v_mfma_f32_16x16x32_bf16 v[84:87], v[160:163], v[220:223], v[84:87]
	v_mfma_f32_16x16x32_bf16 v[80:83], v[160:163], v[224:227], v[80:83]
	s_setprio 0
	s_cbranch_vccz .Lgu_sk11
	s_cmp_eq_u32 s28, 0
	s_cbranch_scc0 .Lgu_sk11
	s_add_u32 m0, s40, 0x8000
	s_nop 0
	global_load_lds_dwordx4 v232, s[20:21]
	s_add_u32 m0, s40, 0xa000
	s_nop 0
	global_load_lds_dwordx4 v233, s[20:21]
.Lgu_sk11:
	ds_read_b128 v[160:163], v206 offset:10240
	s_waitcnt lgkmcnt(6)
	s_setprio 1
	v_mfma_f32_16x16x32_bf16 v[76:79], v[164:167], v[212:215], v[76:79]
	v_mfma_f32_16x16x32_bf16 v[72:75], v[164:167], v[216:219], v[72:75]
	v_mfma_f32_16x16x32_bf16 v[68:71], v[164:167], v[220:223], v[68:71]
	v_mfma_f32_16x16x32_bf16 v[64:67], v[164:167], v[224:227], v[64:67]
	s_setprio 0
	s_cbranch_vccz .Lgu_sk12
	s_cmp_eq_u32 s28, 0
	s_cbranch_scc0 .Lgu_sk12
	s_add_u32 m0, s40, 0xc000
	s_nop 0
	global_load_lds_dwordx4 v234, s[20:21]
	s_add_u32 m0, s40, 0xe000
	s_nop 0
	global_load_lds_dwordx4 v235, s[20:21]
; template <int EPI>
; __device__ __forceinline__ void gemm_phase(const Params& p, const u16* __restrict__ A, const u16* __restrict__ Bt, int K, int nN,
;                            u16* __restrict__ Cout, int ldc) {
;     ...
;       GSTEP(0, 2); GSTEP(1, 6); GSTEP(2, 6); GSTEP(3, 6); GSTEP(4, 2); GSTEP(5, 2); GSTEP(6, 2); GSTEP(7, 2);
;       GSTEP(8, 2); GSTEP(9, 2); GSTEP(10, 2); GSTEP(11, 2); GSTEP(12, 2); GSTEP(13, 2); GSTEP(14, 1); GSTEP(15, 0);
.Lgu_sk12:
	ds_read_b128 v[164:167], v206 offset:12288
	s_waitcnt lgkmcnt(2)
	s_setprio 1
	v_mfma_f32_16x16x32_bf16 v[60:63], v[168:171], v[212:215], v[60:63]
	v_mfma_f32_16x16x32_bf16 v[56:59], v[168:171], v[216:219], v[56:59]
	v_mfma_f32_16x16x32_bf16 v[52:55], v[168:171], v[220:223], v[52:55]
	v_mfma_f32_16x16x32_bf16 v[48:51], v[168:171], v[224:227], v[48:51]
	s_setprio 0
	s_cbranch_vccz .Lgu_sk13
	s_cmp_eq_u32 s28, 1
	s_cbranch_scc0 .Lgu_sk13
	s_mov_b32 m0, s40
	s_nop 0
	global_load_lds_dwordx4 v232, s[22:23]
	s_add_u32 m0, s40, 0x2000
	s_nop 0
	global_load_lds_dwordx4 v233, s[22:23]
.Lgu_sk13:
	ds_read_b128 v[168:171], v206 offset:14336
	s_waitcnt lgkmcnt(2)
	s_setprio 1
	v_mfma_f32_16x16x32_bf16 v[44:47], v[160:163], v[212:215], v[44:47]
	v_mfma_f32_16x16x32_bf16 v[40:43], v[160:163], v[216:219], v[40:43]
	v_mfma_f32_16x16x32_bf16 v[36:39], v[160:163], v[220:223], v[36:39]
	v_mfma_f32_16x16x32_bf16 v[32:35], v[160:163], v[224:227], v[32:35]
	s_setprio 0
	s_cbranch_vccz .Lgu_sk14
	s_cmp_eq_u32 s28, 1
	s_cbranch_scc0 .Lgu_sk14
	s_add_u32 m0, s40, 0x4000
	s_nop 0
	global_load_lds_dwordx4 v234, s[22:23]
	s_add_u32 m0, s40, 0x6000
	s_nop 0
	global_load_lds_dwordx4 v235, s[22:23]
.Lgu_sk14:
	ds_read_b128 v[160:163], v206 offset:1024
	s_waitcnt lgkmcnt(2)
	s_setprio 1
	v_mfma_f32_16x16x32_bf16 v[28:31], v[164:167], v[212:215], v[28:31]
	v_mfma_f32_16x16x32_bf16 v[24:27], v[164:167], v[216:219], v[24:27]
	v_mfma_f32_16x16x32_bf16 v[20:23], v[164:167], v[220:223], v[20:23]
	v_mfma_f32_16x16x32_bf16 v[16:19], v[164:167], v[224:227], v[16:19]
	s_setprio 0
	s_cbranch_vccz .Lgu_sk15
	s_cmp_eq_u32 s28, 1
	s_cbranch_scc0 .Lgu_sk15
	s_add_u32 m0, s40, 0x8000
	s_nop 0
	global_load_lds_dwordx4 v232, s[20:21]
	s_add_u32 m0, s40, 0xa000
	s_nop 0
	global_load_lds_dwordx4 v233, s[20:21]
.Lgu_sk15:
	ds_read_b128 v[164:167], v206 offset:3072
	s_waitcnt lgkmcnt(2)
	s_setprio 1
	v_mfma_f32_16x16x32_bf16 v[12:15], v[168:171], v[212:215], v[12:15]
	v_mfma_f32_16x16x32_bf16 v[8:11], v[168:171], v[216:219], v[8:11]
	v_mfma_f32_16x16x32_bf16 v[4:7], v[168:171], v[220:223], v[4:7]
	v_mfma_f32_16x16x32_bf16 v[0:3], v[168:171], v[224:227], v[0:3]
	s_setprio 0
	s_cbranch_vccz .Lgu_sk16
	s_cmp_eq_u32 s28, 1
	s_cbranch_scc0 .Lgu_sk16
	s_add_u32 m0, s40, 0xc000
	s_nop 0
	global_load_lds_dwordx4 v234, s[20:21]
	s_add_u32 m0, s40, 0xe000
	s_nop 0
	global_load_lds_dwordx4 v235, s[20:21]
.Lgu_sk16:
	ds_read_b128 v[144:147], v206 offset:5120
	s_waitcnt lgkmcnt(2)
	s_setprio 1
	v_mfma_f32_16x16x32_bf16 v[124:127], v[160:163], v[128:131], v[124:127]
	v_mfma_f32_16x16x32_bf16 v[120:123], v[160:163], v[132:135], v[120:123]
	v_mfma_f32_16x16x32_bf16 v[116:119], v[160:163], v[136:139], v[116:119]
	v_mfma_f32_16x16x32_bf16 v[112:115], v[160:163], v[140:143], v[112:115]
	s_setprio 0
	ds_read_b128 v[148:151], v206 offset:7168
	s_waitcnt lgkmcnt(2)
	s_setprio 1
	v_mfma_f32_16x16x32_bf16 v[108:111], v[164:167], v[128:131], v[108:111]
	v_mfma_f32_16x16x32_bf16 v[104:107], v[164:167], v[132:135], v[104:107]
	v_mfma_f32_16x16x32_bf16 v[100:103], v[164:167], v[136:139], v[100:103]
	v_mfma_f32_16x16x32_bf16 v[96:99], v[164:167], v[140:143], v[96:99]
	s_setprio 0
	ds_read_b128 v[152:155], v206 offset:9216
	s_waitcnt lgkmcnt(2)
	s_setprio 1
	v_mfma_f32_16x16x32_bf16 v[92:95], v[144:147], v[128:131], v[92:95]
	v_mfma_f32_16x16x32_bf16 v[88:91], v[144:147], v[132:135], v[88:91]
	v_mfma_f32_16x16x32_bf16 v[84:87], v[144:147], v[136:139], v[84:87]
	v_mfma_f32_16x16x32_bf16 v[80:83], v[144:147], v[140:143], v[80:83]
	s_setprio 0
	ds_read_b128 v[144:147], v206 offset:11264
	s_waitcnt lgkmcnt(2)
	s_setprio 1
	v_mfma_f32_16x16x32_bf16 v[76:79], v[148:151], v[128:131], v[76:79]
	v_mfma_f32_16x16x32_bf16 v[72:75], v[148:151], v[132:135], v[72:75]
	v_mfma_f32_16x16x32_bf16 v[68:71], v[148:151], v[136:139], v[68:71]
	v_mfma_f32_16x16x32_bf16 v[64:67], v[148:151], v[140:143], v[64:67]
	s_setprio 0
	ds_read_b128 v[148:151], v206 offset:13312
	s_waitcnt lgkmcnt(2)
	s_setprio 1
	v_mfma_f32_16x16x32_bf16 v[60:63], v[152:155], v[128:131], v[60:63]
	v_mfma_f32_16x16x32_bf16 v[56:59], v[152:155], v[132:135], v[56:59]
	v_mfma_f32_16x16x32_bf16 v[52:55], v[152:155], v[136:139], v[52:55]
	v_mfma_f32_16x16x32_bf16 v[48:51], v[152:155], v[140:143], v[48:51]
	s_setprio 0
	ds_read_b128 v[152:155], v206 offset:15360
	s_waitcnt lgkmcnt(2)
	s_setprio 1
	v_mfma_f32_16x16x32_bf16 v[44:47], v[144:147], v[128:131], v[44:47]
	v_mfma_f32_16x16x32_bf16 v[40:43], v[144:147], v[132:135], v[40:43]
	v_mfma_f32_16x16x32_bf16 v[36:39], v[144:147], v[136:139], v[36:39]
	v_mfma_f32_16x16x32_bf16 v[32:35], v[144:147], v[140:143], v[32:35]
	s_setprio 0
	s_waitcnt vmcnt(0) lgkmcnt(0)
	s_barrier
	v_xor_b32_e32 v208, 0x10000, v208
	v_xor_b32_e32 v206, 0x10000, v206
	ds_read_b128 v[212:215], v208 offset:0
	ds_read_b128 v[216:219], v208 offset:2048
	ds_read_b128 v[220:223], v208 offset:4096
	ds_read_b128 v[224:227], v208 offset:6144
	ds_read_b128 v[228:231], v206 offset:0
	ds_read_b128 v[168:171], v206 offset:2048
	ds_read_b128 v[160:163], v206 offset:4096
	s_add_u32 s25, s25, 0x80
	s_addc_u32 s26, s26, 0
	s_add_u32 s13, s13, 0x80
	s_addc_u32 s24, s24, 0
	s_xor_b32 s40, s40, 0x10000
	s_add_i32 s27, s27, 1
	s_cmp_lg_u32 s27, -1
	s_cselect_b32 s22, s25, s16
	s_cselect_b32 s23, s26, s17
	s_cselect_b32 s20, s13, s18
	s_cselect_b32 s21, s24, s19
	s_cselect_b64 vcc, -1, s[10:11]
	s_cmp_eq_u32 s27, 0
	s_cselect_b64 vcc, 0, vcc
	s_setprio 1
	v_mfma_f32_16x16x32_bf16 v[28:31], v[148:151], v[128:131], v[28:31]
	v_mfma_f32_16x16x32_bf16 v[24:27], v[148:151], v[132:135], v[24:27]
	v_mfma_f32_16x16x32_bf16 v[20:23], v[148:151], v[136:139], v[20:23]
	v_mfma_f32_16x16x32_bf16 v[16:19], v[148:151], v[140:143], v[16:19]
	s_setprio 0
	s_setprio 1
	v_mfma_f32_16x16x32_bf16 v[12:15], v[152:155], v[128:131], v[12:15]
	v_mfma_f32_16x16x32_bf16 v[8:11], v[152:155], v[132:135], v[8:11]
	v_mfma_f32_16x16x32_bf16 v[4:7], v[152:155], v[136:139], v[4:7]
	v_mfma_f32_16x16x32_bf16 v[0:3], v[152:155], v[140:143], v[0:3]
	s_setprio 0
	s_cmp_lg_u32 s27, 0
	s_cbranch_scc1 .Lgu_head
	s_waitcnt lgkmcnt(0)
	s_branch .LBB0_1126
